# P0 overlap version plus a kernel-entry initialisation of its first-iteration flag
# baseline (speedup 1.0000x reference)
; #define LAS __attribute__((address_space(3)))
; #define WSP() ((unsigned char*)(GAS unsigned char*)KARG64(240))
; __device__ __forceinline__ unsigned xb_add(unsigned* p, unsigned v) { return __hip_atomic_fetch_add(p, v, __ATOMIC_RELAXED, __HIP_MEMORY_SCOPE_AGENT); }
; __device__ __forceinline__ unsigned xb_xcc_id() { return (unsigned)__builtin_amdgcn_s_getreg((3 << 11) | 20) & 0xFu; }
; __device__ __forceinline__ XcdBarrier xcd_barrier_post(unsigned* bar, volatile LAS unsigned* st) {
;     XcdBarrier b; b.bar = bar; b.x = xb_xcc_id(); b.st = st;
;     if (threadIdx.x == 0) (void)xb_add(&bar[XB_XCNT(b.x)], 1u);
;     return b;
; __global__ void __launch_bounds__(NWAVES * 64, 2) hybrid_fwd(Params P) {
;     ...
;     const int tid = threadIdx.x, lane = tid & 63, wave = __builtin_amdgcn_readfirstlane(tid >> 6);
;     const int G = gridDim.x, bx = blockIdx.x;
;     const int vcu = (G % 8 == 0) ? (bx % 8) * (G / 8) + bx / 8 : bx;
;     const int gw = bx * NWAVES + wave, NGW = G * NWAVES;
;     const int lo = P.ph_lo, hi = P.ph_hi;
;     if (tid < 64) ((LAS unsigned*)(lds + LDS_X))[tid] = 0u;
;     __syncthreads();
;     XcdBarrier xbar = xcd_barrier_post((unsigned*)(WSP() + WS_BAR), (volatile LAS unsigned*)(lds + LDS_X));
_Z10hybrid_fwd6Params:
	s_mov_b32 s59, 0
	s_load_dwordx2 s[78:79], s[0:1], 0xf8
	v_and_b32_e32 v218, 0x3ff, v0
	s_add_u32 s84, s0, 0x100
	v_readfirstlane_b32 s3, v218
	s_addc_u32 s85, s1, 0
	v_cmp_gt_u32_e64 s[4:5], 64, v218
	v_writelane_b32 v240, s3, 0
	s_and_saveexec_b64 s[6:7], s[4:5]
	v_lshl_add_u32 v1, v218, 2, 0
	v_add_u32_e32 v1, 0x20000, v1
	v_mov_b32_e32 v2, 0
	ds_write_b32 v1, v2
	s_or_b64 exec, exec, s[6:7]
	s_mov_b64 s[6:7], s[0:1]
	s_load_dword s3, s[0:1], 0x100
	s_waitcnt lgkmcnt(0)
	s_barrier
	s_load_dwordx2 s[80:81], s[6:7], 0xf0
	s_getreg_b32 s6, hwreg(HW_REG_XCC_ID, 0, 4)
	v_cmp_eq_u32_e64 s[8:9], 0, v218
	s_waitcnt lgkmcnt(0)
	s_add_u32 s82, s80, 0x80000
	s_addc_u32 s83, s81, 0
	s_and_b32 s87, s6, 15
	s_mov_b64 s[6:7], exec
	v_writelane_b32 v240, s8, 1
	s_nop 1
	v_writelane_b32 v240, s9, 2
	s_and_b64 s[8:9], s[6:7], s[8:9]
	s_mov_b64 exec, s[8:9]
	s_cbranch_execz .LBB0_5
	s_mov_b64 s[8:9], exec
	v_mbcnt_lo_u32_b32 v1, s8, 0
	v_mbcnt_hi_u32_b32 v1, s9, v1
	v_cmp_eq_u32_e32 vcc, 0, v1
	s_and_b64 s[10:11], exec, vcc
	s_mov_b64 exec, s[10:11]
	s_cbranch_execz .LBB0_5
	s_lshl_b32 s10, s87, 8
	s_bcnt1_i32_b64 s8, s[8:9]
	v_mov_b32_e32 v1, s10
	v_mov_b32_e32 v2, s8
	global_atomic_add v1, v2, s[82:83] offset:1024
